# epilogue de-serialisation: the four sub-LN weight loads of the attention epilogue issued together with one wait instead of load-wait four times
# baseline (speedup 1.0000x reference)
; __device__ __forceinline__ unsigned f2bf(float f) { unsigned u = __builtin_bit_cast(unsigned, f); return (u + 0x7fffu + ((u >> 16) & 1u)) >> 16; }
; __device__ __forceinline__ int crow(int r, int hi) { return (r & 3) + 8 * (r >> 2) + 4 * hi; }
; __device__ __forceinline__ void attn_unit(const bf16* __restrict__ Qb, const bf16* __restrict__ Kh, const bf16* __restrict__ Vh, int klat0, int nlt, int kctx0, int NT,
;                                           float lam, float post, const float* __restrict__ subw, bf16* __restrict__ Ob, char* lds) {
;     ...
;   __syncthreads();
;   if (sbr == 0) {
;     float sw[4];
; #pragma unroll
;     for (int d0 = 0; d0 < 4; ++d0) sw[d0] = subw[d0 * 32 + r32_e] * post;
;     bf16* Ow = Ob + (long)(wq_e * 32) * DM;
; #pragma unroll
;     for (int r = 0; r < 16; ++r) { const int orow = crow(r, hi_e); float v[4]; float ss = 0.f;
; #pragma unroll
;       for (int d0 = 0; d0 < 4; ++d0) { v[d0] = o[d0][r] - lam * X[(wq_e * 32 + orow) * 128 + d0 * 32 + r32_e]; ss += v[d0] * v[d0]; }
;       ss += __shfl_xor(ss, 1); ss += __shfl_xor(ss, 2); ss += __shfl_xor(ss, 4); ss += __shfl_xor(ss, 8); ss += __shfl_xor(ss, 16);
;       const float rs = 1.0f / sqrtf(ss * (1.0f / 128.0f) + LN_EPS);
; #pragma unroll
;       for (int d0 = 0; d0 < 4; ++d0) Ow[(long)orow * DM + d0 * 32 + r32_e] = (bf16)f2bf(v[d0] * rs * sw[d0]); }
.LBB0_795:
	s_andn2_b64 vcc, exec, s[6:7]
	s_waitcnt lgkmcnt(0)
	s_barrier
	s_cbranch_vccnz .LBB0_714
	v_lshlrev_b32_e32 v30, 2, v139
	v_ashrrev_i32_e32 v139, 31, v138
	v_lshl_add_u64 v[4:5], v[138:139], 2, s[2:3]
	global_load_dword v8, v[4:5], off
	global_load_dword v244, v[4:5], off offset:128
	global_load_dword v245, v[4:5], off offset:256
	global_load_dword v246, v[4:5], off offset:384
	s_lshl_b64 s[0:1], s[4:5], 12
	v_readlane_b32 s4, v251, 21
	s_add_u32 s0, s4, s0
	v_readlane_b32 s4, v251, 22
	s_addc_u32 s1, s4, s1
	s_mov_b32 s4, 0xf800000
	s_add_u32 s0, s0, s16
	s_addc_u32 s1, s1, 0
	v_ashrrev_i32_e32 v31, 31, v30
	v_add_u32_e32 v28, 8, v30
	v_add_u32_e32 v26, 9, v30
	v_add_u32_e32 v24, 10, v30
	v_add_u32_e32 v22, 11, v30
	v_add_u32_e32 v20, 16, v30
	v_add_u32_e32 v18, 17, v30
	v_add_u32_e32 v16, 18, v30
	v_add_u32_e32 v14, 19, v30
	v_add_u32_e32 v12, 24, v30
	v_add_u32_e32 v10, 25, v30
	v_add_u32_e32 v6, 26, v30
	v_add_u32_e32 v2, 27, v30
	v_ashrrev_i32_e32 v29, 31, v28
	v_ashrrev_i32_e32 v27, 31, v26
	v_ashrrev_i32_e32 v25, 31, v24
	v_ashrrev_i32_e32 v23, 31, v22
	v_ashrrev_i32_e32 v21, 31, v20
	v_ashrrev_i32_e32 v19, 31, v18
	v_ashrrev_i32_e32 v17, 31, v16
	v_ashrrev_i32_e32 v15, 31, v14
	v_ashrrev_i32_e32 v13, 31, v12
	v_ashrrev_i32_e32 v11, 31, v10
	v_ashrrev_i32_e32 v7, 31, v6
	v_ashrrev_i32_e32 v3, 31, v2
	s_waitcnt vmcnt(0)
	v_mul_f32_e32 v34, v161, v8
	v_mul_f32_e32 v35, v161, v244
	v_mul_f32_e32 v36, v161, v245
	v_lshlrev_b32_e32 v8, 5, v88
	v_ashrrev_i32_e32 v9, 31, v8
	v_mul_f32_e32 v37, v161, v246
	v_lshlrev_b64 v[4:5], 12, v[8:9]
	v_add_u32_e32 v9, v30, v8
	v_lshl_add_u32 v9, v9, 7, v138
	v_lshl_add_u32 v9, v9, 2, 0
	ds_read2_b32 v[98:99], v9 offset1:32
	v_lshl_add_u64 v[4:5], s[0:1], 0, v[4:5]
	v_lshl_add_u64 v[4:5], v[138:139], 1, v[4:5]
	s_waitcnt lgkmcnt(0)
	v_fma_f32 v88, -v160, v98, v108
	v_fma_f32 v97, -v160, v99, v109
	ds_read2_b32 v[98:99], v9 offset0:64 offset1:96
	v_mul_f32_e32 v100, v97, v97
	v_fmac_f32_e32 v100, v88, v88
	s_waitcnt lgkmcnt(0)
	v_fma_f32 v9, -v160, v98, v106
	v_fmac_f32_e32 v100, v9, v9
	v_fma_f32 v101, -v160, v99, v107
	v_fmac_f32_e32 v100, v101, v101
	s_nop 1
	v_mov_b32_dpp v98, v100 quad_perm:[1,0,3,2] row_mask:0xf bank_mask:0xf
	s_waitcnt lgkmcnt(0)
	v_add_f32_e32 v98, v100, v98
	s_nop 1
	v_mov_b32_dpp v99, v98 quad_perm:[2,3,0,1] row_mask:0xf bank_mask:0xf
	s_waitcnt lgkmcnt(0)
	v_add_f32_e32 v98, v98, v99
	s_nop 1
	v_mov_b32_dpp v99, v98 row_half_mirror row_mask:0xf bank_mask:0xf
	s_waitcnt lgkmcnt(0)
	v_add_f32_e32 v98, v98, v99
	s_nop 1
	v_mov_b32_dpp v99, v98 row_mirror row_mask:0xf bank_mask:0xf
	s_waitcnt lgkmcnt(0)
	v_add_f32_e32 v98, v98, v99
	v_mov_b32_e32 v99, v98
	s_nop 1
	v_permlane16_swap_b32_e32 v98, v99
	s_waitcnt lgkmcnt(0)
	v_add_f32_e32 v98, v98, v99
	v_fmamk_f32 v98, v98, 0x3c000000, v179
	v_cmp_gt_f32_e32 vcc, s4, v98
	v_mul_f32_e32 v99, 0x4f800000, v98
	s_nop 0
	v_cndmask_b32_e32 v98, v98, v99, vcc
	v_sqrt_f32_e32 v99, v98
	s_nop 0
	v_add_u32_e32 v100, -1, v99
	v_fma_f32 v102, -v100, v99, v98
	v_cmp_ge_f32_e64 s[0:1], 0, v102
	v_add_u32_e32 v102, 1, v99
	s_nop 0
	v_cndmask_b32_e64 v100, v99, v100, s[0:1]
	v_fma_f32 v99, -v102, v99, v98
	v_cmp_lt_f32_e64 s[0:1], 0, v99
	s_nop 1
	v_cndmask_b32_e64 v99, v100, v102, s[0:1]
	v_mul_f32_e32 v100, 0x37800000, v99
	v_cndmask_b32_e32 v99, v99, v100, vcc
	v_cmp_class_f32_e32 vcc, v98, v180
	s_nop 1
	v_cndmask_b32_e32 v98, v99, v98, vcc
	v_div_scale_f32 v99, s[0:1], v98, v98, 1.0
	v_rcp_f32_e32 v100, v99
	s_nop 0
	v_fma_f32 v102, -v99, v100, 1.0
	v_fmac_f32_e32 v100, v102, v100
	v_div_scale_f32 v102, vcc, 1.0, v98, 1.0
	v_mul_f32_e32 v103, v102, v100
	v_fma_f32 v104, -v99, v103, v102
	v_fmac_f32_e32 v103, v104, v100
	v_fma_f32 v99, -v99, v103, v102
	v_div_fmas_f32 v99, v99, v100, v103
	v_div_fixup_f32 v100, v99, v98, 1.0
	v_lshlrev_b64 v[98:99], 12, v[30:31]
	v_mul_f32_e32 v31, v88, v100
	v_mul_f32_e32 v31, v34, v31
	v_bfe_u32 v88, v31, 16, 1
	v_lshl_add_u64 v[98:99], v[4:5], 0, v[98:99]
	v_add3_u32 v31, v31, v88, s70
	global_store_short_d16_hi v[98:99], v31, off
	v_mul_f32_e32 v31, v97, v100
	v_mul_f32_e32 v31, v35, v31
	v_bfe_u32 v88, v31, 16, 1
	v_mul_f32_e32 v9, v9, v100
	v_add3_u32 v31, v31, v88, s70
	v_mul_f32_e32 v9, v36, v9
	global_store_short_d16_hi v[98:99], v31, off offset:64
	v_bfe_u32 v31, v9, 16, 1
	v_add3_u32 v9, v9, v31, s70
	global_store_short_d16_hi v[98:99], v9, off offset:128
	v_mul_f32_e32 v9, v101, v100
	v_mul_f32_e32 v9, v37, v9
	v_bfe_u32 v31, v9, 16, 1
	v_add3_u32 v9, v9, v31, s70
	global_store_short_d16_hi v[98:99], v9, off offset:192
	v_or_b32_e32 v98, 1, v30
	v_add_u32_e32 v9, v98, v8
	v_lshl_add_u32 v9, v9, 7, v138
	v_lshl_add_u32 v9, v9, 2, 0
	ds_read2_b32 v[100:101], v9 offset1:32
	s_waitcnt lgkmcnt(0)
	v_fma_f32 v88, -v160, v101, v96
	ds_read2_b32 v[96:97], v9 offset0:64 offset1:96
	v_fma_f32 v31, -v160, v100, v95
	v_mul_f32_e32 v95, v88, v88
	v_fmac_f32_e32 v95, v31, v31
	s_waitcnt lgkmcnt(0)
	v_fma_f32 v9, -v160, v96, v93
	v_fmac_f32_e32 v95, v9, v9
	v_fma_f32 v93, -v160, v97, v94
	v_fmac_f32_e32 v95, v93, v93
	s_nop 1
	v_mov_b32_dpp v94, v95 quad_perm:[1,0,3,2] row_mask:0xf bank_mask:0xf
	s_waitcnt lgkmcnt(0)
	v_add_f32_e32 v94, v95, v94
	s_nop 1
	v_mov_b32_dpp v95, v94 quad_perm:[2,3,0,1] row_mask:0xf bank_mask:0xf
	s_waitcnt lgkmcnt(0)
	v_add_f32_e32 v94, v94, v95
	s_nop 1
	v_mov_b32_dpp v95, v94 row_half_mirror row_mask:0xf bank_mask:0xf
	s_waitcnt lgkmcnt(0)
	v_add_f32_e32 v94, v94, v95
	s_nop 1
	v_mov_b32_dpp v95, v94 row_mirror row_mask:0xf bank_mask:0xf
	s_waitcnt lgkmcnt(0)
	v_add_f32_e32 v94, v94, v95
	v_mov_b32_e32 v95, v94
	s_nop 1
	v_permlane16_swap_b32_e32 v94, v95
	s_waitcnt lgkmcnt(0)
; __device__ __forceinline__ unsigned f2bf(float f) { unsigned u = __builtin_bit_cast(unsigned, f); return (u + 0x7fffu + ((u >> 16) & 1u)) >> 16; }
; __device__ __forceinline__ int crow(int r, int hi) { return (r & 3) + 8 * (r >> 2) + 4 * hi; }
; __device__ __forceinline__ void attn_unit(const bf16* __restrict__ Qb, const bf16* __restrict__ Kh, const bf16* __restrict__ Vh, int klat0, int nlt, int kctx0, int NT,
;                                           float lam, float post, const float* __restrict__ subw, bf16* __restrict__ Ob, char* lds) {
;     ...
;     for (int r = 0; r < 16; ++r) { const int orow = crow(r, hi_e); float v[4]; float ss = 0.f;
; #pragma unroll
;       for (int d0 = 0; d0 < 4; ++d0) { v[d0] = o[d0][r] - lam * X[(wq_e * 32 + orow) * 128 + d0 * 32 + r32_e]; ss += v[d0] * v[d0]; }
;       ss += __shfl_xor(ss, 1); ss += __shfl_xor(ss, 2); ss += __shfl_xor(ss, 4); ss += __shfl_xor(ss, 8); ss += __shfl_xor(ss, 16);
;       const float rs = 1.0f / sqrtf(ss * (1.0f / 128.0f) + LN_EPS);
; #pragma unroll
;       for (int d0 = 0; d0 < 4; ++d0) Ow[(long)orow * DM + d0 * 32 + r32_e] = (bf16)f2bf(v[d0] * rs * sw[d0]); }
	v_add_f32_e32 v94, v94, v95
	v_fmamk_f32 v94, v94, 0x3c000000, v179
	v_cmp_gt_f32_e32 vcc, s4, v94
	v_mul_f32_e32 v95, 0x4f800000, v94
	s_nop 0
	v_cndmask_b32_e32 v94, v94, v95, vcc
	v_sqrt_f32_e32 v95, v94
	s_nop 0
	v_add_u32_e32 v96, -1, v95
	v_fma_f32 v97, -v96, v95, v94
	v_cmp_ge_f32_e64 s[0:1], 0, v97
	v_add_u32_e32 v97, 1, v95
	s_nop 0
	v_cndmask_b32_e64 v96, v95, v96, s[0:1]
	v_fma_f32 v95, -v97, v95, v94
	v_cmp_lt_f32_e64 s[0:1], 0, v95
	s_nop 1
	v_cndmask_b32_e64 v95, v96, v97, s[0:1]
	v_mul_f32_e32 v96, 0x37800000, v95
	v_cndmask_b32_e32 v95, v95, v96, vcc
	v_cmp_class_f32_e32 vcc, v94, v180
	s_nop 1
	v_cndmask_b32_e32 v94, v95, v94, vcc
	v_div_scale_f32 v95, s[0:1], v94, v94, 1.0
	v_rcp_f32_e32 v96, v95
	s_nop 0
	v_fma_f32 v97, -v95, v96, 1.0
	v_fmac_f32_e32 v96, v97, v96
	v_div_scale_f32 v97, vcc, 1.0, v94, 1.0
	v_mul_f32_e32 v99, v97, v96
	v_fma_f32 v100, -v95, v99, v97
	v_fmac_f32_e32 v99, v100, v96
	v_fma_f32 v95, -v95, v99, v97
	v_div_fmas_f32 v95, v95, v96, v99
	v_div_fixup_f32 v96, v95, v94, 1.0
	v_mul_f32_e32 v31, v31, v96
	v_ashrrev_i32_e32 v99, 31, v98
	v_mul_f32_e32 v31, v34, v31
	v_lshlrev_b64 v[94:95], 12, v[98:99]
	v_bfe_u32 v97, v31, 16, 1
	v_lshl_add_u64 v[94:95], v[4:5], 0, v[94:95]
	v_add3_u32 v31, v31, v97, s70
	global_store_short_d16_hi v[94:95], v31, off
	v_mul_f32_e32 v31, v88, v96
	v_mul_f32_e32 v31, v35, v31
	v_bfe_u32 v88, v31, 16, 1
	v_mul_f32_e32 v9, v9, v96
	v_add3_u32 v31, v31, v88, s70
	v_mul_f32_e32 v9, v36, v9
	global_store_short_d16_hi v[94:95], v31, off offset:64
	v_bfe_u32 v31, v9, 16, 1
	v_add3_u32 v9, v9, v31, s70
	global_store_short_d16_hi v[94:95], v9, off offset:128
	v_mul_f32_e32 v9, v93, v96
	v_mul_f32_e32 v9, v37, v9
	v_bfe_u32 v31, v9, 16, 1
	v_add3_u32 v9, v9, v31, s70
	v_or_b32_e32 v88, 2, v30
	global_store_short_d16_hi v[94:95], v9, off offset:192
	v_add_u32_e32 v9, v88, v8
	v_lshl_add_u32 v9, v9, 7, v138
	v_lshl_add_u32 v9, v9, 2, 0
	ds_read2_b32 v[94:95], v9 offset1:32
	v_or_b32_e32 v30, 3, v30
	s_waitcnt lgkmcnt(0)
	v_fma_f32 v31, -v160, v94, v91
	v_fma_f32 v91, -v160, v95, v92
	ds_read2_b32 v[92:93], v9 offset0:64 offset1:96
	v_mul_f32_e32 v94, v91, v91
	v_fmac_f32_e32 v94, v31, v31
	s_waitcnt lgkmcnt(0)
	v_fma_f32 v9, -v160, v92, v89
	v_fmac_f32_e32 v94, v9, v9
	v_fma_f32 v90, -v160, v93, v90
	v_fmac_f32_e32 v94, v90, v90
	s_nop 1
	v_mov_b32_dpp v89, v94 quad_perm:[1,0,3,2] row_mask:0xf bank_mask:0xf
	s_waitcnt lgkmcnt(0)
	v_add_f32_e32 v89, v94, v89
	s_nop 1
	v_mov_b32_dpp v92, v89 quad_perm:[2,3,0,1] row_mask:0xf bank_mask:0xf
	s_waitcnt lgkmcnt(0)
	v_add_f32_e32 v89, v89, v92
	s_nop 1
	v_mov_b32_dpp v92, v89 row_half_mirror row_mask:0xf bank_mask:0xf
	s_waitcnt lgkmcnt(0)
	v_add_f32_e32 v89, v89, v92
	s_nop 1
	v_mov_b32_dpp v92, v89 row_mirror row_mask:0xf bank_mask:0xf
	s_waitcnt lgkmcnt(0)
	v_add_f32_e32 v89, v89, v92
	v_mov_b32_e32 v92, v89
	s_nop 1
	v_permlane16_swap_b32_e32 v89, v92
	s_waitcnt lgkmcnt(0)
	v_add_f32_e32 v89, v89, v92
	v_fmamk_f32 v89, v89, 0x3c000000, v179
	v_cmp_gt_f32_e32 vcc, s4, v89
	v_mul_f32_e32 v92, 0x4f800000, v89
	s_nop 0
	v_cndmask_b32_e32 v89, v89, v92, vcc
	v_sqrt_f32_e32 v92, v89
	s_nop 0
	v_add_u32_e32 v93, -1, v92
	v_fma_f32 v94, -v93, v92, v89
	v_cmp_ge_f32_e64 s[0:1], 0, v94
	v_add_u32_e32 v94, 1, v92
	s_nop 0
	v_cndmask_b32_e64 v93, v92, v93, s[0:1]
	v_fma_f32 v92, -v94, v92, v89
	v_cmp_lt_f32_e64 s[0:1], 0, v92
	s_nop 1
	v_cndmask_b32_e64 v92, v93, v94, s[0:1]
	v_mul_f32_e32 v93, 0x37800000, v92
	v_cndmask_b32_e32 v92, v92, v93, vcc
	v_cmp_class_f32_e32 vcc, v89, v180
	s_nop 1
	v_cndmask_b32_e32 v89, v92, v89, vcc
	v_div_scale_f32 v92, s[0:1], v89, v89, 1.0
	v_rcp_f32_e32 v93, v92
	s_nop 0
	v_fma_f32 v94, -v92, v93, 1.0
	v_fmac_f32_e32 v93, v94, v93
	v_div_scale_f32 v94, vcc, 1.0, v89, 1.0
	v_mul_f32_e32 v95, v94, v93
	v_fma_f32 v96, -v92, v95, v94
	v_fmac_f32_e32 v95, v96, v93
	v_fma_f32 v92, -v92, v95, v94
	v_div_fmas_f32 v92, v92, v93, v95
	v_div_fixup_f32 v92, v92, v89, 1.0
	v_mul_f32_e32 v31, v31, v92
	v_ashrrev_i32_e32 v89, 31, v88
	v_mul_f32_e32 v31, v34, v31
	v_lshlrev_b64 v[88:89], 12, v[88:89]
	v_bfe_u32 v93, v31, 16, 1
	v_lshl_add_u64 v[88:89], v[4:5], 0, v[88:89]
	v_add3_u32 v31, v31, v93, s70
	global_store_short_d16_hi v[88:89], v31, off
	v_mul_f32_e32 v31, v91, v92
	v_mul_f32_e32 v31, v35, v31
	v_bfe_u32 v91, v31, 16, 1
	v_mul_f32_e32 v9, v9, v92
	v_add3_u32 v31, v31, v91, s70
	v_mul_f32_e32 v9, v36, v9
	global_store_short_d16_hi v[88:89], v31, off offset:64
	v_bfe_u32 v31, v9, 16, 1
	v_add3_u32 v9, v9, v31, s70
	global_store_short_d16_hi v[88:89], v9, off offset:128
	v_mul_f32_e32 v9, v90, v92
	v_mul_f32_e32 v9, v37, v9
	v_bfe_u32 v31, v9, 16, 1
	v_add3_u32 v9, v9, v31, s70
	global_store_short_d16_hi v[88:89], v9, off offset:192
	v_add_u32_e32 v9, v30, v8
	v_lshl_add_u32 v9, v9, 7, v138
	v_lshl_add_u32 v9, v9, 2, 0
	ds_read2_b32 v[88:89], v9 offset1:32
	s_waitcnt lgkmcnt(0)
	v_fma_f32 v88, -v160, v88, v86
	v_fma_f32 v89, -v160, v89, v87
	ds_read2_b32 v[86:87], v9 offset0:64 offset1:96
	v_mul_f32_e32 v31, v89, v89
	v_fmac_f32_e32 v31, v88, v88
	s_waitcnt lgkmcnt(0)
	v_fma_f32 v9, -v160, v86, v84
	v_fmac_f32_e32 v31, v9, v9
	v_fma_f32 v84, -v160, v87, v85
	v_fmac_f32_e32 v31, v84, v84
	s_nop 1
	v_mov_b32_dpp v85, v31 quad_perm:[1,0,3,2] row_mask:0xf bank_mask:0xf
	s_waitcnt lgkmcnt(0)
	v_add_f32_e32 v31, v31, v85
	s_nop 1
	v_mov_b32_dpp v85, v31 quad_perm:[2,3,0,1] row_mask:0xf bank_mask:0xf
	s_waitcnt lgkmcnt(0)
	v_add_f32_e32 v31, v31, v85
	s_nop 1
	v_mov_b32_dpp v85, v31 row_half_mirror row_mask:0xf bank_mask:0xf
	s_waitcnt lgkmcnt(0)
	v_add_f32_e32 v31, v31, v85
	s_nop 1
	v_mov_b32_dpp v85, v31 row_mirror row_mask:0xf bank_mask:0xf
	s_waitcnt lgkmcnt(0)
; __device__ __forceinline__ unsigned f2bf(float f) { unsigned u = __builtin_bit_cast(unsigned, f); return (u + 0x7fffu + ((u >> 16) & 1u)) >> 16; }
; __device__ __forceinline__ int crow(int r, int hi) { return (r & 3) + 8 * (r >> 2) + 4 * hi; }
; __device__ __forceinline__ void attn_unit(const bf16* __restrict__ Qb, const bf16* __restrict__ Kh, const bf16* __restrict__ Vh, int klat0, int nlt, int kctx0, int NT,
;                                           float lam, float post, const float* __restrict__ subw, bf16* __restrict__ Ob, char* lds) {
;     ...
;     for (int r = 0; r < 16; ++r) { const int orow = crow(r, hi_e); float v[4]; float ss = 0.f;
; #pragma unroll
;       for (int d0 = 0; d0 < 4; ++d0) { v[d0] = o[d0][r] - lam * X[(wq_e * 32 + orow) * 128 + d0 * 32 + r32_e]; ss += v[d0] * v[d0]; }
;       ss += __shfl_xor(ss, 1); ss += __shfl_xor(ss, 2); ss += __shfl_xor(ss, 4); ss += __shfl_xor(ss, 8); ss += __shfl_xor(ss, 16);
;       const float rs = 1.0f / sqrtf(ss * (1.0f / 128.0f) + LN_EPS);
; #pragma unroll
;       for (int d0 = 0; d0 < 4; ++d0) Ow[(long)orow * DM + d0 * 32 + r32_e] = (bf16)f2bf(v[d0] * rs * sw[d0]); }
	v_add_f32_e32 v31, v31, v85
	v_mov_b32_e32 v85, v31
	s_nop 1
	v_permlane16_swap_b32_e32 v31, v85
	s_waitcnt lgkmcnt(0)
	v_add_f32_e32 v31, v31, v85
	v_fmamk_f32 v31, v31, 0x3c000000, v179
	v_cmp_gt_f32_e32 vcc, s4, v31
	v_mul_f32_e32 v85, 0x4f800000, v31
	s_nop 0
	v_cndmask_b32_e32 v31, v31, v85, vcc
	v_sqrt_f32_e32 v85, v31
	s_nop 0
	v_add_u32_e32 v86, -1, v85
	v_fma_f32 v87, -v86, v85, v31
	v_cmp_ge_f32_e64 s[0:1], 0, v87
	v_add_u32_e32 v87, 1, v85
	s_nop 0
	v_cndmask_b32_e64 v86, v85, v86, s[0:1]
	v_fma_f32 v85, -v87, v85, v31
	v_cmp_lt_f32_e64 s[0:1], 0, v85
	s_nop 1
	v_cndmask_b32_e64 v85, v86, v87, s[0:1]
	v_mul_f32_e32 v86, 0x37800000, v85
	v_cndmask_b32_e32 v85, v85, v86, vcc
	v_cmp_class_f32_e32 vcc, v31, v180
	s_nop 1
	v_cndmask_b32_e32 v31, v85, v31, vcc
	v_div_scale_f32 v85, s[0:1], v31, v31, 1.0
	v_rcp_f32_e32 v86, v85
	s_nop 0
	v_fma_f32 v87, -v85, v86, 1.0
	v_fmac_f32_e32 v86, v87, v86
	v_div_scale_f32 v87, vcc, 1.0, v31, 1.0
	v_mul_f32_e32 v90, v87, v86
	v_fma_f32 v91, -v85, v90, v87
	v_fmac_f32_e32 v90, v91, v86
	v_fma_f32 v85, -v85, v90, v87
	v_div_fmas_f32 v85, v85, v86, v90
	v_div_fixup_f32 v85, v85, v31, 1.0
	v_mul_f32_e32 v86, v88, v85
	v_ashrrev_i32_e32 v31, 31, v30
	v_mul_f32_e32 v86, v34, v86
	v_lshlrev_b64 v[30:31], 12, v[30:31]
	v_bfe_u32 v87, v86, 16, 1
	v_lshl_add_u64 v[30:31], v[4:5], 0, v[30:31]
	v_add3_u32 v86, v86, v87, s70
	global_store_short_d16_hi v[30:31], v86, off
	v_mul_f32_e32 v86, v89, v85
	v_mul_f32_e32 v86, v35, v86
	v_bfe_u32 v87, v86, 16, 1
	v_mul_f32_e32 v9, v9, v85
	v_add3_u32 v86, v86, v87, s70
	v_mul_f32_e32 v9, v36, v9
	global_store_short_d16_hi v[30:31], v86, off offset:64
	v_bfe_u32 v86, v9, 16, 1
	v_add3_u32 v9, v9, v86, s70
	global_store_short_d16_hi v[30:31], v9, off offset:128
	v_mul_f32_e32 v9, v84, v85
	v_mul_f32_e32 v9, v37, v9
	v_bfe_u32 v84, v9, 16, 1
	v_add3_u32 v9, v9, v84, s70
	global_store_short_d16_hi v[30:31], v9, off offset:192
	v_add_u32_e32 v9, v28, v8
	v_lshl_add_u32 v9, v9, 7, v138
	v_lshl_add_u32 v9, v9, 2, 0
	ds_read2_b32 v[30:31], v9 offset1:32
	v_lshlrev_b64 v[28:29], 12, v[28:29]
	v_lshl_add_u64 v[28:29], v[4:5], 0, v[28:29]
	s_waitcnt lgkmcnt(0)
	v_fma_f32 v82, -v160, v30, v82
	v_fma_f32 v83, -v160, v31, v83
	ds_read2_b32 v[30:31], v9 offset0:64 offset1:96
	v_mul_f32_e32 v84, v83, v83
	v_fmac_f32_e32 v84, v82, v82
	s_waitcnt lgkmcnt(0)
	v_fma_f32 v9, -v160, v30, v65
	v_fmac_f32_e32 v84, v9, v9
	v_fma_f32 v30, -v160, v31, v81
	v_fmac_f32_e32 v84, v30, v30
	s_nop 1
	v_mov_b32_dpp v31, v84 quad_perm:[1,0,3,2] row_mask:0xf bank_mask:0xf
	s_waitcnt lgkmcnt(0)
	v_add_f32_e32 v31, v84, v31
	s_nop 1
	v_mov_b32_dpp v65, v31 quad_perm:[2,3,0,1] row_mask:0xf bank_mask:0xf
	s_waitcnt lgkmcnt(0)
	v_add_f32_e32 v31, v31, v65
	s_nop 1
	v_mov_b32_dpp v65, v31 row_half_mirror row_mask:0xf bank_mask:0xf
	s_waitcnt lgkmcnt(0)
	v_add_f32_e32 v31, v31, v65
	s_nop 1
	v_mov_b32_dpp v65, v31 row_mirror row_mask:0xf bank_mask:0xf
	s_waitcnt lgkmcnt(0)
	v_add_f32_e32 v31, v31, v65
	v_mov_b32_e32 v65, v31
	s_nop 1
	v_permlane16_swap_b32_e32 v31, v65
	s_waitcnt lgkmcnt(0)
	v_add_f32_e32 v31, v31, v65
	v_fmamk_f32 v31, v31, 0x3c000000, v179
	v_cmp_gt_f32_e32 vcc, s4, v31
	v_mul_f32_e32 v65, 0x4f800000, v31
	s_nop 0
	v_cndmask_b32_e32 v31, v31, v65, vcc
	v_sqrt_f32_e32 v65, v31
	s_nop 0
	v_add_u32_e32 v81, -1, v65
	v_fma_f32 v84, -v81, v65, v31
	v_cmp_ge_f32_e64 s[0:1], 0, v84
	v_add_u32_e32 v84, 1, v65
	s_nop 0
	v_cndmask_b32_e64 v81, v65, v81, s[0:1]
	v_fma_f32 v65, -v84, v65, v31
	v_cmp_lt_f32_e64 s[0:1], 0, v65
	s_nop 1
	v_cndmask_b32_e64 v65, v81, v84, s[0:1]
	v_mul_f32_e32 v81, 0x37800000, v65
	v_cndmask_b32_e32 v65, v65, v81, vcc
	v_cmp_class_f32_e32 vcc, v31, v180
	s_nop 1
	v_cndmask_b32_e32 v31, v65, v31, vcc
	v_div_scale_f32 v65, s[0:1], v31, v31, 1.0
	v_rcp_f32_e32 v81, v65
	s_nop 0
	v_fma_f32 v84, -v65, v81, 1.0
	v_fmac_f32_e32 v81, v84, v81
	v_div_scale_f32 v84, vcc, 1.0, v31, 1.0
	v_mul_f32_e32 v85, v84, v81
	v_fma_f32 v86, -v65, v85, v84
	v_fmac_f32_e32 v85, v86, v81
	v_fma_f32 v65, -v65, v85, v84
	v_div_fmas_f32 v65, v65, v81, v85
	v_div_fixup_f32 v31, v65, v31, 1.0
	v_mul_f32_e32 v65, v82, v31
	v_mul_f32_e32 v65, v34, v65
	v_bfe_u32 v81, v65, 16, 1
	v_add3_u32 v65, v65, v81, s70
	global_store_short_d16_hi v[28:29], v65, off
	v_mul_f32_e32 v65, v83, v31
	v_mul_f32_e32 v65, v35, v65
	v_bfe_u32 v81, v65, 16, 1
	v_mul_f32_e32 v9, v9, v31
	v_add3_u32 v65, v65, v81, s70
	v_mul_f32_e32 v9, v36, v9
	global_store_short_d16_hi v[28:29], v65, off offset:64
	v_bfe_u32 v65, v9, 16, 1
	v_add3_u32 v9, v9, v65, s70
	global_store_short_d16_hi v[28:29], v9, off offset:128
	v_mul_f32_e32 v9, v30, v31
	v_mul_f32_e32 v9, v37, v9
	v_bfe_u32 v30, v9, 16, 1
	v_add3_u32 v9, v9, v30, s70
	global_store_short_d16_hi v[28:29], v9, off offset:192
	v_add_u32_e32 v9, v26, v8
	v_lshl_add_u32 v9, v9, 7, v138
	v_lshl_add_u32 v9, v9, 2, 0
	ds_read2_b32 v[28:29], v9 offset1:32
	v_lshlrev_b64 v[26:27], 12, v[26:27]
	v_lshl_add_u64 v[26:27], v[4:5], 0, v[26:27]
	s_waitcnt lgkmcnt(0)
	v_fma_f32 v30, -v160, v28, v79
	v_fma_f32 v31, -v160, v29, v80
	ds_read2_b32 v[28:29], v9 offset0:64 offset1:96
	v_mul_f32_e32 v65, v31, v31
	v_fmac_f32_e32 v65, v30, v30
	s_waitcnt lgkmcnt(0)
	v_fma_f32 v9, -v160, v28, v63
	v_fmac_f32_e32 v65, v9, v9
	v_fma_f32 v28, -v160, v29, v64
	v_fmac_f32_e32 v65, v28, v28
	s_nop 1
	v_mov_b32_dpp v29, v65 quad_perm:[1,0,3,2] row_mask:0xf bank_mask:0xf
	s_waitcnt lgkmcnt(0)
	v_add_f32_e32 v29, v65, v29
	s_nop 1
	v_mov_b32_dpp v63, v29 quad_perm:[2,3,0,1] row_mask:0xf bank_mask:0xf
	s_waitcnt lgkmcnt(0)
	v_add_f32_e32 v29, v29, v63
	s_nop 1
	v_mov_b32_dpp v63, v29 row_half_mirror row_mask:0xf bank_mask:0xf
	s_waitcnt lgkmcnt(0)
; __device__ __forceinline__ unsigned f2bf(float f) { unsigned u = __builtin_bit_cast(unsigned, f); return (u + 0x7fffu + ((u >> 16) & 1u)) >> 16; }
; __device__ __forceinline__ int crow(int r, int hi) { return (r & 3) + 8 * (r >> 2) + 4 * hi; }
; __device__ __forceinline__ void attn_unit(const bf16* __restrict__ Qb, const bf16* __restrict__ Kh, const bf16* __restrict__ Vh, int klat0, int nlt, int kctx0, int NT,
;                                           float lam, float post, const float* __restrict__ subw, bf16* __restrict__ Ob, char* lds) {
;     ...
;     for (int r = 0; r < 16; ++r) { const int orow = crow(r, hi_e); float v[4]; float ss = 0.f;
; #pragma unroll
;       for (int d0 = 0; d0 < 4; ++d0) { v[d0] = o[d0][r] - lam * X[(wq_e * 32 + orow) * 128 + d0 * 32 + r32_e]; ss += v[d0] * v[d0]; }
;       ss += __shfl_xor(ss, 1); ss += __shfl_xor(ss, 2); ss += __shfl_xor(ss, 4); ss += __shfl_xor(ss, 8); ss += __shfl_xor(ss, 16);
;       const float rs = 1.0f / sqrtf(ss * (1.0f / 128.0f) + LN_EPS);
; #pragma unroll
;       for (int d0 = 0; d0 < 4; ++d0) Ow[(long)orow * DM + d0 * 32 + r32_e] = (bf16)f2bf(v[d0] * rs * sw[d0]); }
	v_add_f32_e32 v29, v29, v63
	s_nop 1
	v_mov_b32_dpp v63, v29 row_mirror row_mask:0xf bank_mask:0xf
	s_waitcnt lgkmcnt(0)
	v_add_f32_e32 v29, v29, v63
	v_mov_b32_e32 v63, v29
	s_nop 1
	v_permlane16_swap_b32_e32 v29, v63
	s_waitcnt lgkmcnt(0)
	v_add_f32_e32 v29, v29, v63
	v_fmamk_f32 v29, v29, 0x3c000000, v179
	v_cmp_gt_f32_e32 vcc, s4, v29
	v_mul_f32_e32 v63, 0x4f800000, v29
	s_nop 0
	v_cndmask_b32_e32 v29, v29, v63, vcc
	v_sqrt_f32_e32 v63, v29
	s_nop 0
	v_add_u32_e32 v64, -1, v63
	v_fma_f32 v65, -v64, v63, v29
	v_cmp_ge_f32_e64 s[0:1], 0, v65
	v_add_u32_e32 v65, 1, v63
	s_nop 0
	v_cndmask_b32_e64 v64, v63, v64, s[0:1]
	v_fma_f32 v63, -v65, v63, v29
	v_cmp_lt_f32_e64 s[0:1], 0, v63
	s_nop 1
	v_cndmask_b32_e64 v63, v64, v65, s[0:1]
	v_mul_f32_e32 v64, 0x37800000, v63
	v_cndmask_b32_e32 v63, v63, v64, vcc
	v_cmp_class_f32_e32 vcc, v29, v180
	s_nop 1
	v_cndmask_b32_e32 v29, v63, v29, vcc
	v_div_scale_f32 v63, s[0:1], v29, v29, 1.0
	v_rcp_f32_e32 v64, v63
	s_nop 0
	v_fma_f32 v65, -v63, v64, 1.0
	v_fmac_f32_e32 v64, v65, v64
	v_div_scale_f32 v65, vcc, 1.0, v29, 1.0
	v_mul_f32_e32 v79, v65, v64
	v_fma_f32 v80, -v63, v79, v65
	v_fmac_f32_e32 v79, v80, v64
	v_fma_f32 v63, -v63, v79, v65
	v_div_fmas_f32 v63, v63, v64, v79
	v_div_fixup_f32 v29, v63, v29, 1.0
	v_mul_f32_e32 v30, v30, v29
	v_mul_f32_e32 v30, v34, v30
	v_bfe_u32 v63, v30, 16, 1
	v_add3_u32 v30, v30, v63, s70
	global_store_short_d16_hi v[26:27], v30, off
	v_mul_f32_e32 v30, v31, v29
	v_mul_f32_e32 v30, v35, v30
	v_bfe_u32 v31, v30, 16, 1
	v_mul_f32_e32 v9, v9, v29
	v_add3_u32 v30, v30, v31, s70
	v_mul_f32_e32 v9, v36, v9
	global_store_short_d16_hi v[26:27], v30, off offset:64
	v_bfe_u32 v30, v9, 16, 1
	v_add3_u32 v9, v9, v30, s70
	global_store_short_d16_hi v[26:27], v9, off offset:128
	v_mul_f32_e32 v9, v28, v29
	v_mul_f32_e32 v9, v37, v9
	v_bfe_u32 v28, v9, 16, 1
	v_add3_u32 v9, v9, v28, s70
	global_store_short_d16_hi v[26:27], v9, off offset:192
	v_add_u32_e32 v9, v24, v8
	v_lshl_add_u32 v9, v9, 7, v138
	v_lshl_add_u32 v9, v9, 2, 0
	ds_read2_b32 v[26:27], v9 offset1:32
	v_lshlrev_b64 v[24:25], 12, v[24:25]
	v_lshl_add_u64 v[24:25], v[4:5], 0, v[24:25]
	s_waitcnt lgkmcnt(0)
	v_fma_f32 v28, -v160, v26, v77
	v_fma_f32 v29, -v160, v27, v78
	ds_read2_b32 v[26:27], v9 offset0:64 offset1:96
	v_mul_f32_e32 v30, v29, v29
	v_fmac_f32_e32 v30, v28, v28
	s_waitcnt lgkmcnt(0)
	v_fma_f32 v9, -v160, v26, v61
	v_fmac_f32_e32 v30, v9, v9
	v_fma_f32 v26, -v160, v27, v62
	v_fmac_f32_e32 v30, v26, v26
	s_nop 1
	v_mov_b32_dpp v27, v30 quad_perm:[1,0,3,2] row_mask:0xf bank_mask:0xf
	s_waitcnt lgkmcnt(0)
	v_add_f32_e32 v27, v30, v27
	s_nop 1
	v_mov_b32_dpp v30, v27 quad_perm:[2,3,0,1] row_mask:0xf bank_mask:0xf
	s_waitcnt lgkmcnt(0)
	v_add_f32_e32 v27, v27, v30
	s_nop 1
	v_mov_b32_dpp v30, v27 row_half_mirror row_mask:0xf bank_mask:0xf
	s_waitcnt lgkmcnt(0)
	v_add_f32_e32 v27, v27, v30
	s_nop 1
	v_mov_b32_dpp v30, v27 row_mirror row_mask:0xf bank_mask:0xf
	s_waitcnt lgkmcnt(0)
	v_add_f32_e32 v27, v27, v30
	v_mov_b32_e32 v30, v27
	s_nop 1
	v_permlane16_swap_b32_e32 v27, v30
	s_waitcnt lgkmcnt(0)
	v_add_f32_e32 v27, v27, v30
	v_fmamk_f32 v27, v27, 0x3c000000, v179
	v_cmp_gt_f32_e32 vcc, s4, v27
	v_mul_f32_e32 v30, 0x4f800000, v27
	s_nop 0
	v_cndmask_b32_e32 v27, v27, v30, vcc
	v_sqrt_f32_e32 v30, v27
	s_nop 0
	v_add_u32_e32 v31, -1, v30
	v_fma_f32 v61, -v31, v30, v27
	v_cmp_ge_f32_e64 s[0:1], 0, v61
	v_add_u32_e32 v61, 1, v30
	s_nop 0
	v_cndmask_b32_e64 v31, v30, v31, s[0:1]
	v_fma_f32 v30, -v61, v30, v27
	v_cmp_lt_f32_e64 s[0:1], 0, v30
	s_nop 1
	v_cndmask_b32_e64 v30, v31, v61, s[0:1]
	v_mul_f32_e32 v31, 0x37800000, v30
	v_cndmask_b32_e32 v30, v30, v31, vcc
	v_cmp_class_f32_e32 vcc, v27, v180
	s_nop 1
	v_cndmask_b32_e32 v27, v30, v27, vcc
	v_div_scale_f32 v30, s[0:1], v27, v27, 1.0
	v_rcp_f32_e32 v31, v30
	s_nop 0
	v_fma_f32 v61, -v30, v31, 1.0
	v_fmac_f32_e32 v31, v61, v31
	v_div_scale_f32 v61, vcc, 1.0, v27, 1.0
	v_mul_f32_e32 v62, v61, v31
	v_fma_f32 v63, -v30, v62, v61
	v_fmac_f32_e32 v62, v63, v31
	v_fma_f32 v30, -v30, v62, v61
	v_div_fmas_f32 v30, v30, v31, v62
	v_div_fixup_f32 v27, v30, v27, 1.0
	v_mul_f32_e32 v28, v28, v27
	v_mul_f32_e32 v28, v34, v28
	v_bfe_u32 v30, v28, 16, 1
	v_add3_u32 v28, v28, v30, s70
	global_store_short_d16_hi v[24:25], v28, off
	v_mul_f32_e32 v28, v29, v27
	v_mul_f32_e32 v28, v35, v28
	v_bfe_u32 v29, v28, 16, 1
	v_mul_f32_e32 v9, v9, v27
	v_add3_u32 v28, v28, v29, s70
	v_mul_f32_e32 v9, v36, v9
	global_store_short_d16_hi v[24:25], v28, off offset:64
	v_bfe_u32 v28, v9, 16, 1
	v_add3_u32 v9, v9, v28, s70
	global_store_short_d16_hi v[24:25], v9, off offset:128
	v_mul_f32_e32 v9, v26, v27
	v_mul_f32_e32 v9, v37, v9
	v_bfe_u32 v26, v9, 16, 1
	v_add3_u32 v9, v9, v26, s70
	global_store_short_d16_hi v[24:25], v9, off offset:192
	v_add_u32_e32 v9, v22, v8
	v_lshl_add_u32 v9, v9, 7, v138
	v_lshl_add_u32 v9, v9, 2, 0
	ds_read2_b32 v[24:25], v9 offset1:32
	v_lshlrev_b64 v[22:23], 12, v[22:23]
	v_lshl_add_u64 v[22:23], v[4:5], 0, v[22:23]
	s_waitcnt lgkmcnt(0)
	v_fma_f32 v26, -v160, v24, v75
	v_fma_f32 v27, -v160, v25, v76
	ds_read2_b32 v[24:25], v9 offset0:64 offset1:96
	v_mul_f32_e32 v28, v27, v27
	v_fmac_f32_e32 v28, v26, v26
	s_waitcnt lgkmcnt(0)
	v_fma_f32 v9, -v160, v24, v60
	v_fmac_f32_e32 v28, v9, v9
	v_fma_f32 v24, -v160, v25, v49
	v_fmac_f32_e32 v28, v24, v24
	s_nop 1
	v_mov_b32_dpp v25, v28 quad_perm:[1,0,3,2] row_mask:0xf bank_mask:0xf
	s_waitcnt lgkmcnt(0)
	v_add_f32_e32 v25, v28, v25
	s_nop 1
	v_mov_b32_dpp v28, v25 quad_perm:[2,3,0,1] row_mask:0xf bank_mask:0xf
	s_waitcnt lgkmcnt(0)
	v_add_f32_e32 v25, v25, v28
	s_nop 1
	v_mov_b32_dpp v28, v25 row_half_mirror row_mask:0xf bank_mask:0xf
	s_waitcnt lgkmcnt(0)
; __device__ __forceinline__ unsigned f2bf(float f) { unsigned u = __builtin_bit_cast(unsigned, f); return (u + 0x7fffu + ((u >> 16) & 1u)) >> 16; }
; __device__ __forceinline__ int crow(int r, int hi) { return (r & 3) + 8 * (r >> 2) + 4 * hi; }
; __device__ __forceinline__ void attn_unit(const bf16* __restrict__ Qb, const bf16* __restrict__ Kh, const bf16* __restrict__ Vh, int klat0, int nlt, int kctx0, int NT,
;                                           float lam, float post, const float* __restrict__ subw, bf16* __restrict__ Ob, char* lds) {
;     ...
;     for (int r = 0; r < 16; ++r) { const int orow = crow(r, hi_e); float v[4]; float ss = 0.f;
; #pragma unroll
;       for (int d0 = 0; d0 < 4; ++d0) { v[d0] = o[d0][r] - lam * X[(wq_e * 32 + orow) * 128 + d0 * 32 + r32_e]; ss += v[d0] * v[d0]; }
;       ss += __shfl_xor(ss, 1); ss += __shfl_xor(ss, 2); ss += __shfl_xor(ss, 4); ss += __shfl_xor(ss, 8); ss += __shfl_xor(ss, 16);
;       const float rs = 1.0f / sqrtf(ss * (1.0f / 128.0f) + LN_EPS);
; #pragma unroll
;       for (int d0 = 0; d0 < 4; ++d0) Ow[(long)orow * DM + d0 * 32 + r32_e] = (bf16)f2bf(v[d0] * rs * sw[d0]); }
	v_add_f32_e32 v25, v25, v28
	s_nop 1
	v_mov_b32_dpp v28, v25 row_mirror row_mask:0xf bank_mask:0xf
	s_waitcnt lgkmcnt(0)
	v_add_f32_e32 v25, v25, v28
	v_mov_b32_e32 v28, v25
	s_nop 1
	v_permlane16_swap_b32_e32 v25, v28
	s_waitcnt lgkmcnt(0)
	v_add_f32_e32 v25, v25, v28
	v_fmamk_f32 v25, v25, 0x3c000000, v179
	v_cmp_gt_f32_e32 vcc, s4, v25
	v_mul_f32_e32 v28, 0x4f800000, v25
	s_nop 0
	v_cndmask_b32_e32 v25, v25, v28, vcc
	v_sqrt_f32_e32 v28, v25
	s_nop 0
	v_add_u32_e32 v29, -1, v28
	v_fma_f32 v30, -v29, v28, v25
	v_cmp_ge_f32_e64 s[0:1], 0, v30
	v_add_u32_e32 v30, 1, v28
	s_nop 0
	v_cndmask_b32_e64 v29, v28, v29, s[0:1]
	v_fma_f32 v28, -v30, v28, v25
	v_cmp_lt_f32_e64 s[0:1], 0, v28
	s_nop 1
	v_cndmask_b32_e64 v28, v29, v30, s[0:1]
	v_mul_f32_e32 v29, 0x37800000, v28
	v_cndmask_b32_e32 v28, v28, v29, vcc
	v_cmp_class_f32_e32 vcc, v25, v180
	s_nop 1
	v_cndmask_b32_e32 v25, v28, v25, vcc
	v_div_scale_f32 v28, s[0:1], v25, v25, 1.0
	v_rcp_f32_e32 v29, v28
	s_nop 0
	v_fma_f32 v30, -v28, v29, 1.0
	v_fmac_f32_e32 v29, v30, v29
	v_div_scale_f32 v30, vcc, 1.0, v25, 1.0
	v_mul_f32_e32 v31, v30, v29
	v_fma_f32 v49, -v28, v31, v30
	v_fmac_f32_e32 v31, v49, v29
	v_fma_f32 v28, -v28, v31, v30
	v_div_fmas_f32 v28, v28, v29, v31
	v_div_fixup_f32 v25, v28, v25, 1.0
	v_mul_f32_e32 v26, v26, v25
	v_mul_f32_e32 v26, v34, v26
	v_bfe_u32 v28, v26, 16, 1
	v_add3_u32 v26, v26, v28, s70
	global_store_short_d16_hi v[22:23], v26, off
	v_mul_f32_e32 v26, v27, v25
	v_mul_f32_e32 v26, v35, v26
	v_bfe_u32 v27, v26, 16, 1
	v_mul_f32_e32 v9, v9, v25
	v_add3_u32 v26, v26, v27, s70
	v_mul_f32_e32 v9, v36, v9
	global_store_short_d16_hi v[22:23], v26, off offset:64
	v_bfe_u32 v26, v9, 16, 1
	v_add3_u32 v9, v9, v26, s70
	global_store_short_d16_hi v[22:23], v9, off offset:128
	v_mul_f32_e32 v9, v24, v25
	v_mul_f32_e32 v9, v37, v9
	v_bfe_u32 v24, v9, 16, 1
	v_add3_u32 v9, v9, v24, s70
	global_store_short_d16_hi v[22:23], v9, off offset:192
	v_add_u32_e32 v9, v20, v8
	v_lshl_add_u32 v9, v9, 7, v138
	v_lshl_add_u32 v9, v9, 2, 0
	ds_read2_b32 v[22:23], v9 offset1:32
	v_lshlrev_b64 v[20:21], 12, v[20:21]
	v_lshl_add_u64 v[20:21], v[4:5], 0, v[20:21]
	s_waitcnt lgkmcnt(0)
	v_fma_f32 v24, -v160, v22, v73
	v_fma_f32 v25, -v160, v23, v74
	ds_read2_b32 v[22:23], v9 offset0:64 offset1:96
	v_mul_f32_e32 v26, v25, v25
	v_fmac_f32_e32 v26, v24, v24
	s_waitcnt lgkmcnt(0)
	v_fma_f32 v9, -v160, v22, v59
	v_fmac_f32_e32 v26, v9, v9
	v_fma_f32 v22, -v160, v23, v48
	v_fmac_f32_e32 v26, v22, v22
	s_nop 1
	v_mov_b32_dpp v23, v26 quad_perm:[1,0,3,2] row_mask:0xf bank_mask:0xf
	s_waitcnt lgkmcnt(0)
	v_add_f32_e32 v23, v26, v23
	s_nop 1
	v_mov_b32_dpp v26, v23 quad_perm:[2,3,0,1] row_mask:0xf bank_mask:0xf
	s_waitcnt lgkmcnt(0)
	v_add_f32_e32 v23, v23, v26
	s_nop 1
	v_mov_b32_dpp v26, v23 row_half_mirror row_mask:0xf bank_mask:0xf
	s_waitcnt lgkmcnt(0)
	v_add_f32_e32 v23, v23, v26
	s_nop 1
	v_mov_b32_dpp v26, v23 row_mirror row_mask:0xf bank_mask:0xf
	s_waitcnt lgkmcnt(0)
	v_add_f32_e32 v23, v23, v26
	v_mov_b32_e32 v26, v23
	s_nop 1
	v_permlane16_swap_b32_e32 v23, v26
	s_waitcnt lgkmcnt(0)
	v_add_f32_e32 v23, v23, v26
	v_fmamk_f32 v23, v23, 0x3c000000, v179
	v_cmp_gt_f32_e32 vcc, s4, v23
	v_mul_f32_e32 v26, 0x4f800000, v23
	s_nop 0
	v_cndmask_b32_e32 v23, v23, v26, vcc
	v_sqrt_f32_e32 v26, v23
	s_nop 0
	v_add_u32_e32 v27, -1, v26
	v_fma_f32 v28, -v27, v26, v23
	v_cmp_ge_f32_e64 s[0:1], 0, v28
	v_add_u32_e32 v28, 1, v26
	s_nop 0
	v_cndmask_b32_e64 v27, v26, v27, s[0:1]
	v_fma_f32 v26, -v28, v26, v23
	v_cmp_lt_f32_e64 s[0:1], 0, v26
	s_nop 1
	v_cndmask_b32_e64 v26, v27, v28, s[0:1]
	v_mul_f32_e32 v27, 0x37800000, v26
	v_cndmask_b32_e32 v26, v26, v27, vcc
	v_cmp_class_f32_e32 vcc, v23, v180
	s_nop 1
	v_cndmask_b32_e32 v23, v26, v23, vcc
	v_div_scale_f32 v26, s[0:1], v23, v23, 1.0
	v_rcp_f32_e32 v27, v26
	s_nop 0
	v_fma_f32 v28, -v26, v27, 1.0
	v_fmac_f32_e32 v27, v28, v27
	v_div_scale_f32 v28, vcc, 1.0, v23, 1.0
	v_mul_f32_e32 v29, v28, v27
	v_fma_f32 v30, -v26, v29, v28
	v_fmac_f32_e32 v29, v30, v27
	v_fma_f32 v26, -v26, v29, v28
	v_div_fmas_f32 v26, v26, v27, v29
	v_div_fixup_f32 v23, v26, v23, 1.0
	v_mul_f32_e32 v24, v24, v23
	v_mul_f32_e32 v24, v34, v24
	v_bfe_u32 v26, v24, 16, 1
	v_add3_u32 v24, v24, v26, s70
	global_store_short_d16_hi v[20:21], v24, off
	v_mul_f32_e32 v24, v25, v23
	v_mul_f32_e32 v24, v35, v24
	v_bfe_u32 v25, v24, 16, 1
	v_mul_f32_e32 v9, v9, v23
	v_add3_u32 v24, v24, v25, s70
	v_mul_f32_e32 v9, v36, v9
	global_store_short_d16_hi v[20:21], v24, off offset:64
	v_bfe_u32 v24, v9, 16, 1
	v_add3_u32 v9, v9, v24, s70
	global_store_short_d16_hi v[20:21], v9, off offset:128
	v_mul_f32_e32 v9, v22, v23
	v_mul_f32_e32 v9, v37, v9
	v_bfe_u32 v22, v9, 16, 1
	v_add3_u32 v9, v9, v22, s70
	global_store_short_d16_hi v[20:21], v9, off offset:192
	v_add_u32_e32 v9, v18, v8
	v_lshl_add_u32 v9, v9, 7, v138
	v_lshl_add_u32 v9, v9, 2, 0
	ds_read2_b32 v[20:21], v9 offset1:32
	v_lshlrev_b64 v[18:19], 12, v[18:19]
	v_lshl_add_u64 v[18:19], v[4:5], 0, v[18:19]
	s_waitcnt lgkmcnt(0)
	v_fma_f32 v22, -v160, v20, v72
	v_fma_f32 v23, -v160, v21, v58
	ds_read2_b32 v[20:21], v9 offset0:64 offset1:96
	v_mul_f32_e32 v24, v23, v23
	v_fmac_f32_e32 v24, v22, v22
	s_waitcnt lgkmcnt(0)
	v_fma_f32 v9, -v160, v20, v57
	v_fmac_f32_e32 v24, v9, v9
	v_fma_f32 v20, -v160, v21, v47
	v_fmac_f32_e32 v24, v20, v20
	s_nop 1
	v_mov_b32_dpp v21, v24 quad_perm:[1,0,3,2] row_mask:0xf bank_mask:0xf
	s_waitcnt lgkmcnt(0)
	v_add_f32_e32 v21, v24, v21
	s_nop 1
	v_mov_b32_dpp v24, v21 quad_perm:[2,3,0,1] row_mask:0xf bank_mask:0xf
	s_waitcnt lgkmcnt(0)
	v_add_f32_e32 v21, v21, v24
	s_nop 1
	v_mov_b32_dpp v24, v21 row_half_mirror row_mask:0xf bank_mask:0xf
	s_waitcnt lgkmcnt(0)
; __device__ __forceinline__ unsigned f2bf(float f) { unsigned u = __builtin_bit_cast(unsigned, f); return (u + 0x7fffu + ((u >> 16) & 1u)) >> 16; }
; __device__ __forceinline__ int crow(int r, int hi) { return (r & 3) + 8 * (r >> 2) + 4 * hi; }
; __device__ __forceinline__ void attn_unit(const bf16* __restrict__ Qb, const bf16* __restrict__ Kh, const bf16* __restrict__ Vh, int klat0, int nlt, int kctx0, int NT,
;                                           float lam, float post, const float* __restrict__ subw, bf16* __restrict__ Ob, char* lds) {
;     ...
;     for (int r = 0; r < 16; ++r) { const int orow = crow(r, hi_e); float v[4]; float ss = 0.f;
; #pragma unroll
;       for (int d0 = 0; d0 < 4; ++d0) { v[d0] = o[d0][r] - lam * X[(wq_e * 32 + orow) * 128 + d0 * 32 + r32_e]; ss += v[d0] * v[d0]; }
;       ss += __shfl_xor(ss, 1); ss += __shfl_xor(ss, 2); ss += __shfl_xor(ss, 4); ss += __shfl_xor(ss, 8); ss += __shfl_xor(ss, 16);
;       const float rs = 1.0f / sqrtf(ss * (1.0f / 128.0f) + LN_EPS);
; #pragma unroll
;       for (int d0 = 0; d0 < 4; ++d0) Ow[(long)orow * DM + d0 * 32 + r32_e] = (bf16)f2bf(v[d0] * rs * sw[d0]); }
	v_add_f32_e32 v21, v21, v24
	s_nop 1
	v_mov_b32_dpp v24, v21 row_mirror row_mask:0xf bank_mask:0xf
	s_waitcnt lgkmcnt(0)
	v_add_f32_e32 v21, v21, v24
	v_mov_b32_e32 v24, v21
	s_nop 1
	v_permlane16_swap_b32_e32 v21, v24
	s_waitcnt lgkmcnt(0)
	v_add_f32_e32 v21, v21, v24
	v_fmamk_f32 v21, v21, 0x3c000000, v179
	v_cmp_gt_f32_e32 vcc, s4, v21
	v_mul_f32_e32 v24, 0x4f800000, v21
	s_nop 0
	v_cndmask_b32_e32 v21, v21, v24, vcc
	v_sqrt_f32_e32 v24, v21
	s_nop 0
	v_add_u32_e32 v25, -1, v24
	v_fma_f32 v26, -v25, v24, v21
	v_cmp_ge_f32_e64 s[0:1], 0, v26
	v_add_u32_e32 v26, 1, v24
	s_nop 0
	v_cndmask_b32_e64 v25, v24, v25, s[0:1]
	v_fma_f32 v24, -v26, v24, v21
	v_cmp_lt_f32_e64 s[0:1], 0, v24
	s_nop 1
	v_cndmask_b32_e64 v24, v25, v26, s[0:1]
	v_mul_f32_e32 v25, 0x37800000, v24
	v_cndmask_b32_e32 v24, v24, v25, vcc
	v_cmp_class_f32_e32 vcc, v21, v180
	s_nop 1
	v_cndmask_b32_e32 v21, v24, v21, vcc
	v_div_scale_f32 v24, s[0:1], v21, v21, 1.0
	v_rcp_f32_e32 v25, v24
	s_nop 0
	v_fma_f32 v26, -v24, v25, 1.0
	v_fmac_f32_e32 v25, v26, v25
	v_div_scale_f32 v26, vcc, 1.0, v21, 1.0
	v_mul_f32_e32 v27, v26, v25
	v_fma_f32 v28, -v24, v27, v26
	v_fmac_f32_e32 v27, v28, v25
	v_fma_f32 v24, -v24, v27, v26
	v_div_fmas_f32 v24, v24, v25, v27
	v_div_fixup_f32 v21, v24, v21, 1.0
	v_mul_f32_e32 v22, v22, v21
	v_mul_f32_e32 v22, v34, v22
	v_bfe_u32 v24, v22, 16, 1
	v_add3_u32 v22, v22, v24, s70
	global_store_short_d16_hi v[18:19], v22, off
	v_mul_f32_e32 v22, v23, v21
	v_mul_f32_e32 v22, v35, v22
	v_bfe_u32 v23, v22, 16, 1
	v_mul_f32_e32 v9, v9, v21
	v_add3_u32 v22, v22, v23, s70
	v_mul_f32_e32 v9, v36, v9
	global_store_short_d16_hi v[18:19], v22, off offset:64
	v_bfe_u32 v22, v9, 16, 1
	v_add3_u32 v9, v9, v22, s70
	global_store_short_d16_hi v[18:19], v9, off offset:128
	v_mul_f32_e32 v9, v20, v21
	v_mul_f32_e32 v9, v37, v9
	v_bfe_u32 v20, v9, 16, 1
	v_add3_u32 v9, v9, v20, s70
	global_store_short_d16_hi v[18:19], v9, off offset:192
	v_add_u32_e32 v9, v16, v8
	v_lshl_add_u32 v9, v9, 7, v138
	v_lshl_add_u32 v9, v9, 2, 0
	ds_read2_b32 v[18:19], v9 offset1:32
	v_lshlrev_b64 v[16:17], 12, v[16:17]
	v_lshl_add_u64 v[16:17], v[4:5], 0, v[16:17]
	s_waitcnt lgkmcnt(0)
	v_fma_f32 v20, -v160, v18, v71
	v_fma_f32 v21, -v160, v19, v56
	ds_read2_b32 v[18:19], v9 offset0:64 offset1:96
	v_mul_f32_e32 v22, v21, v21
	v_fmac_f32_e32 v22, v20, v20
	s_waitcnt lgkmcnt(0)
	v_fma_f32 v9, -v160, v18, v55
	v_fmac_f32_e32 v22, v9, v9
	v_fma_f32 v18, -v160, v19, v46
	v_fmac_f32_e32 v22, v18, v18
	s_nop 1
	v_mov_b32_dpp v19, v22 quad_perm:[1,0,3,2] row_mask:0xf bank_mask:0xf
	s_waitcnt lgkmcnt(0)
	v_add_f32_e32 v19, v22, v19
	s_nop 1
	v_mov_b32_dpp v22, v19 quad_perm:[2,3,0,1] row_mask:0xf bank_mask:0xf
	s_waitcnt lgkmcnt(0)
	v_add_f32_e32 v19, v19, v22
	s_nop 1
	v_mov_b32_dpp v22, v19 row_half_mirror row_mask:0xf bank_mask:0xf
	s_waitcnt lgkmcnt(0)
	v_add_f32_e32 v19, v19, v22
	s_nop 1
	v_mov_b32_dpp v22, v19 row_mirror row_mask:0xf bank_mask:0xf
	s_waitcnt lgkmcnt(0)
	v_add_f32_e32 v19, v19, v22
	v_mov_b32_e32 v22, v19
	s_nop 1
	v_permlane16_swap_b32_e32 v19, v22
	s_waitcnt lgkmcnt(0)
	v_add_f32_e32 v19, v19, v22
	v_fmamk_f32 v19, v19, 0x3c000000, v179
	v_cmp_gt_f32_e32 vcc, s4, v19
	v_mul_f32_e32 v22, 0x4f800000, v19
	s_nop 0
	v_cndmask_b32_e32 v19, v19, v22, vcc
	v_sqrt_f32_e32 v22, v19
	s_nop 0
	v_add_u32_e32 v23, -1, v22
	v_fma_f32 v24, -v23, v22, v19
	v_cmp_ge_f32_e64 s[0:1], 0, v24
	v_add_u32_e32 v24, 1, v22
	s_nop 0
	v_cndmask_b32_e64 v23, v22, v23, s[0:1]
	v_fma_f32 v22, -v24, v22, v19
	v_cmp_lt_f32_e64 s[0:1], 0, v22
	s_nop 1
	v_cndmask_b32_e64 v22, v23, v24, s[0:1]
	v_mul_f32_e32 v23, 0x37800000, v22
	v_cndmask_b32_e32 v22, v22, v23, vcc
	v_cmp_class_f32_e32 vcc, v19, v180
	s_nop 1
	v_cndmask_b32_e32 v19, v22, v19, vcc
	v_div_scale_f32 v22, s[0:1], v19, v19, 1.0
	v_rcp_f32_e32 v23, v22
	s_nop 0
	v_fma_f32 v24, -v22, v23, 1.0
	v_fmac_f32_e32 v23, v24, v23
	v_div_scale_f32 v24, vcc, 1.0, v19, 1.0
	v_mul_f32_e32 v25, v24, v23
	v_fma_f32 v26, -v22, v25, v24
	v_fmac_f32_e32 v25, v26, v23
	v_fma_f32 v22, -v22, v25, v24
	v_div_fmas_f32 v22, v22, v23, v25
	v_div_fixup_f32 v19, v22, v19, 1.0
	v_mul_f32_e32 v20, v20, v19
	v_mul_f32_e32 v20, v34, v20
	v_bfe_u32 v22, v20, 16, 1
	v_add3_u32 v20, v20, v22, s70
	global_store_short_d16_hi v[16:17], v20, off
	v_mul_f32_e32 v20, v21, v19
	v_mul_f32_e32 v20, v35, v20
	v_bfe_u32 v21, v20, 16, 1
	v_mul_f32_e32 v9, v9, v19
	v_add3_u32 v20, v20, v21, s70
	v_mul_f32_e32 v9, v36, v9
	global_store_short_d16_hi v[16:17], v20, off offset:64
	v_bfe_u32 v20, v9, 16, 1
	v_add3_u32 v9, v9, v20, s70
	global_store_short_d16_hi v[16:17], v9, off offset:128
	v_mul_f32_e32 v9, v18, v19
	v_mul_f32_e32 v9, v37, v9
	v_bfe_u32 v18, v9, 16, 1
	v_add3_u32 v9, v9, v18, s70
	global_store_short_d16_hi v[16:17], v9, off offset:192
	v_add_u32_e32 v9, v14, v8
	v_lshl_add_u32 v9, v9, 7, v138
	v_lshl_add_u32 v9, v9, 2, 0
	ds_read2_b32 v[16:17], v9 offset1:32
	v_lshlrev_b64 v[14:15], 12, v[14:15]
	v_lshl_add_u64 v[14:15], v[4:5], 0, v[14:15]
	s_waitcnt lgkmcnt(0)
	v_fma_f32 v18, -v160, v16, v70
	v_fma_f32 v19, -v160, v17, v54
	ds_read2_b32 v[16:17], v9 offset0:64 offset1:96
	v_mul_f32_e32 v20, v19, v19
	v_fmac_f32_e32 v20, v18, v18
	s_waitcnt lgkmcnt(0)
	v_fma_f32 v9, -v160, v16, v44
	v_fmac_f32_e32 v20, v9, v9
	v_fma_f32 v16, -v160, v17, v45
	v_fmac_f32_e32 v20, v16, v16
	s_nop 1
	v_mov_b32_dpp v17, v20 quad_perm:[1,0,3,2] row_mask:0xf bank_mask:0xf
	s_waitcnt lgkmcnt(0)
	v_add_f32_e32 v17, v20, v17
	s_nop 1
	v_mov_b32_dpp v20, v17 quad_perm:[2,3,0,1] row_mask:0xf bank_mask:0xf
	s_waitcnt lgkmcnt(0)
	v_add_f32_e32 v17, v17, v20
	s_nop 1
	v_mov_b32_dpp v20, v17 row_half_mirror row_mask:0xf bank_mask:0xf
	s_waitcnt lgkmcnt(0)
; __device__ __forceinline__ unsigned f2bf(float f) { unsigned u = __builtin_bit_cast(unsigned, f); return (u + 0x7fffu + ((u >> 16) & 1u)) >> 16; }
; __device__ __forceinline__ int crow(int r, int hi) { return (r & 3) + 8 * (r >> 2) + 4 * hi; }
; __device__ __forceinline__ void attn_unit(const bf16* __restrict__ Qb, const bf16* __restrict__ Kh, const bf16* __restrict__ Vh, int klat0, int nlt, int kctx0, int NT,
;                                           float lam, float post, const float* __restrict__ subw, bf16* __restrict__ Ob, char* lds) {
;     ...
;     for (int r = 0; r < 16; ++r) { const int orow = crow(r, hi_e); float v[4]; float ss = 0.f;
; #pragma unroll
;       for (int d0 = 0; d0 < 4; ++d0) { v[d0] = o[d0][r] - lam * X[(wq_e * 32 + orow) * 128 + d0 * 32 + r32_e]; ss += v[d0] * v[d0]; }
;       ss += __shfl_xor(ss, 1); ss += __shfl_xor(ss, 2); ss += __shfl_xor(ss, 4); ss += __shfl_xor(ss, 8); ss += __shfl_xor(ss, 16);
;       const float rs = 1.0f / sqrtf(ss * (1.0f / 128.0f) + LN_EPS);
; #pragma unroll
;       for (int d0 = 0; d0 < 4; ++d0) Ow[(long)orow * DM + d0 * 32 + r32_e] = (bf16)f2bf(v[d0] * rs * sw[d0]); }
	v_add_f32_e32 v17, v17, v20
	s_nop 1
	v_mov_b32_dpp v20, v17 row_mirror row_mask:0xf bank_mask:0xf
	s_waitcnt lgkmcnt(0)
	v_add_f32_e32 v17, v17, v20
	v_mov_b32_e32 v20, v17
	s_nop 1
	v_permlane16_swap_b32_e32 v17, v20
	s_waitcnt lgkmcnt(0)
	v_add_f32_e32 v17, v17, v20
	v_fmamk_f32 v17, v17, 0x3c000000, v179
	v_cmp_gt_f32_e32 vcc, s4, v17
	v_mul_f32_e32 v20, 0x4f800000, v17
	s_nop 0
	v_cndmask_b32_e32 v17, v17, v20, vcc
	v_sqrt_f32_e32 v20, v17
	s_nop 0
	v_add_u32_e32 v21, -1, v20
	v_fma_f32 v22, -v21, v20, v17
	v_cmp_ge_f32_e64 s[0:1], 0, v22
	v_add_u32_e32 v22, 1, v20
	s_nop 0
	v_cndmask_b32_e64 v21, v20, v21, s[0:1]
	v_fma_f32 v20, -v22, v20, v17
	v_cmp_lt_f32_e64 s[0:1], 0, v20
	s_nop 1
	v_cndmask_b32_e64 v20, v21, v22, s[0:1]
	v_mul_f32_e32 v21, 0x37800000, v20
	v_cndmask_b32_e32 v20, v20, v21, vcc
	v_cmp_class_f32_e32 vcc, v17, v180
	s_nop 1
	v_cndmask_b32_e32 v17, v20, v17, vcc
	v_div_scale_f32 v20, s[0:1], v17, v17, 1.0
	v_rcp_f32_e32 v21, v20
	s_nop 0
	v_fma_f32 v22, -v20, v21, 1.0
	v_fmac_f32_e32 v21, v22, v21
	v_div_scale_f32 v22, vcc, 1.0, v17, 1.0
	v_mul_f32_e32 v23, v22, v21
	v_fma_f32 v24, -v20, v23, v22
	v_fmac_f32_e32 v23, v24, v21
	v_fma_f32 v20, -v20, v23, v22
	v_div_fmas_f32 v20, v20, v21, v23
	v_div_fixup_f32 v17, v20, v17, 1.0
	v_mul_f32_e32 v18, v18, v17
	v_mul_f32_e32 v18, v34, v18
	v_bfe_u32 v20, v18, 16, 1
	v_add3_u32 v18, v18, v20, s70
	global_store_short_d16_hi v[14:15], v18, off
	v_mul_f32_e32 v18, v19, v17
	v_mul_f32_e32 v18, v35, v18
	v_bfe_u32 v19, v18, 16, 1
	v_mul_f32_e32 v9, v9, v17
	v_add3_u32 v18, v18, v19, s70
	v_mul_f32_e32 v9, v36, v9
	global_store_short_d16_hi v[14:15], v18, off offset:64
	v_bfe_u32 v18, v9, 16, 1
	v_add3_u32 v9, v9, v18, s70
	global_store_short_d16_hi v[14:15], v9, off offset:128
	v_mul_f32_e32 v9, v16, v17
	v_mul_f32_e32 v9, v37, v9
	v_bfe_u32 v16, v9, 16, 1
	v_add3_u32 v9, v9, v16, s70
	global_store_short_d16_hi v[14:15], v9, off offset:192
	v_add_u32_e32 v9, v12, v8
	v_lshl_add_u32 v9, v9, 7, v138
	v_lshl_add_u32 v9, v9, 2, 0
	ds_read2_b32 v[14:15], v9 offset1:32
	v_lshlrev_b64 v[12:13], 12, v[12:13]
	v_lshl_add_u64 v[12:13], v[4:5], 0, v[12:13]
	s_waitcnt lgkmcnt(0)
	v_fma_f32 v16, -v160, v14, v69
	v_fma_f32 v17, -v160, v15, v53
	ds_read2_b32 v[14:15], v9 offset0:64 offset1:96
	v_mul_f32_e32 v18, v17, v17
	v_fmac_f32_e32 v18, v16, v16
	s_waitcnt lgkmcnt(0)
	v_fma_f32 v9, -v160, v14, v42
	v_fmac_f32_e32 v18, v9, v9
	v_fma_f32 v14, -v160, v15, v43
	v_fmac_f32_e32 v18, v14, v14
	s_nop 1
	v_mov_b32_dpp v15, v18 quad_perm:[1,0,3,2] row_mask:0xf bank_mask:0xf
	s_waitcnt lgkmcnt(0)
	v_add_f32_e32 v15, v18, v15
	s_nop 1
	v_mov_b32_dpp v18, v15 quad_perm:[2,3,0,1] row_mask:0xf bank_mask:0xf
	s_waitcnt lgkmcnt(0)
	v_add_f32_e32 v15, v15, v18
	s_nop 1
	v_mov_b32_dpp v18, v15 row_half_mirror row_mask:0xf bank_mask:0xf
	s_waitcnt lgkmcnt(0)
	v_add_f32_e32 v15, v15, v18
	s_nop 1
	v_mov_b32_dpp v18, v15 row_mirror row_mask:0xf bank_mask:0xf
	s_waitcnt lgkmcnt(0)
	v_add_f32_e32 v15, v15, v18
	v_mov_b32_e32 v18, v15
	s_nop 1
	v_permlane16_swap_b32_e32 v15, v18
	s_waitcnt lgkmcnt(0)
	v_add_f32_e32 v15, v15, v18
	v_fmamk_f32 v15, v15, 0x3c000000, v179
	v_cmp_gt_f32_e32 vcc, s4, v15
	v_mul_f32_e32 v18, 0x4f800000, v15
	s_nop 0
	v_cndmask_b32_e32 v15, v15, v18, vcc
	v_sqrt_f32_e32 v18, v15
	s_nop 0
	v_add_u32_e32 v19, -1, v18
	v_fma_f32 v20, -v19, v18, v15
	v_cmp_ge_f32_e64 s[0:1], 0, v20
	v_add_u32_e32 v20, 1, v18
	s_nop 0
	v_cndmask_b32_e64 v19, v18, v19, s[0:1]
	v_fma_f32 v18, -v20, v18, v15
	v_cmp_lt_f32_e64 s[0:1], 0, v18
	s_nop 1
	v_cndmask_b32_e64 v18, v19, v20, s[0:1]
	v_mul_f32_e32 v19, 0x37800000, v18
	v_cndmask_b32_e32 v18, v18, v19, vcc
	v_cmp_class_f32_e32 vcc, v15, v180
	s_nop 1
	v_cndmask_b32_e32 v15, v18, v15, vcc
	v_div_scale_f32 v18, s[0:1], v15, v15, 1.0
	v_rcp_f32_e32 v19, v18
	s_nop 0
	v_fma_f32 v20, -v18, v19, 1.0
	v_fmac_f32_e32 v19, v20, v19
	v_div_scale_f32 v20, vcc, 1.0, v15, 1.0
	v_mul_f32_e32 v21, v20, v19
	v_fma_f32 v22, -v18, v21, v20
	v_fmac_f32_e32 v21, v22, v19
	v_fma_f32 v18, -v18, v21, v20
	v_div_fmas_f32 v18, v18, v19, v21
	v_div_fixup_f32 v15, v18, v15, 1.0
	v_mul_f32_e32 v16, v16, v15
	v_mul_f32_e32 v16, v34, v16
	v_bfe_u32 v18, v16, 16, 1
	v_add3_u32 v16, v16, v18, s70
	global_store_short_d16_hi v[12:13], v16, off
	v_mul_f32_e32 v16, v17, v15
	v_mul_f32_e32 v16, v35, v16
	v_bfe_u32 v17, v16, 16, 1
	v_mul_f32_e32 v9, v9, v15
	v_add3_u32 v16, v16, v17, s70
	v_mul_f32_e32 v9, v36, v9
	global_store_short_d16_hi v[12:13], v16, off offset:64
	v_bfe_u32 v16, v9, 16, 1
	v_add3_u32 v9, v9, v16, s70
	global_store_short_d16_hi v[12:13], v9, off offset:128
	v_mul_f32_e32 v9, v14, v15
	v_mul_f32_e32 v9, v37, v9
	v_bfe_u32 v14, v9, 16, 1
	v_add3_u32 v9, v9, v14, s70
	global_store_short_d16_hi v[12:13], v9, off offset:192
	v_add_u32_e32 v9, v10, v8
	v_lshl_add_u32 v9, v9, 7, v138
	v_lshl_add_u32 v9, v9, 2, 0
	ds_read2_b32 v[12:13], v9 offset1:32
	v_lshlrev_b64 v[10:11], 12, v[10:11]
	v_lshl_add_u64 v[10:11], v[4:5], 0, v[10:11]
	s_waitcnt lgkmcnt(0)
	v_fma_f32 v14, -v160, v12, v68
	v_fma_f32 v15, -v160, v13, v52
	ds_read2_b32 v[12:13], v9 offset0:64 offset1:96
	v_mul_f32_e32 v16, v15, v15
	v_fmac_f32_e32 v16, v14, v14
	s_waitcnt lgkmcnt(0)
	v_fma_f32 v9, -v160, v12, v40
	v_fmac_f32_e32 v16, v9, v9
	v_fma_f32 v12, -v160, v13, v41
	v_fmac_f32_e32 v16, v12, v12
	s_nop 1
	v_mov_b32_dpp v13, v16 quad_perm:[1,0,3,2] row_mask:0xf bank_mask:0xf
	s_waitcnt lgkmcnt(0)
	v_add_f32_e32 v13, v16, v13
	s_nop 1
	v_mov_b32_dpp v16, v13 quad_perm:[2,3,0,1] row_mask:0xf bank_mask:0xf
	s_waitcnt lgkmcnt(0)
	v_add_f32_e32 v13, v13, v16
	s_nop 1
	v_mov_b32_dpp v16, v13 row_half_mirror row_mask:0xf bank_mask:0xf
	s_waitcnt lgkmcnt(0)
; __device__ __forceinline__ unsigned f2bf(float f) { unsigned u = __builtin_bit_cast(unsigned, f); return (u + 0x7fffu + ((u >> 16) & 1u)) >> 16; }
; __device__ __forceinline__ int crow(int r, int hi) { return (r & 3) + 8 * (r >> 2) + 4 * hi; }
; __device__ __forceinline__ void attn_unit(const bf16* __restrict__ Qb, const bf16* __restrict__ Kh, const bf16* __restrict__ Vh, int klat0, int nlt, int kctx0, int NT,
;                                           float lam, float post, const float* __restrict__ subw, bf16* __restrict__ Ob, char* lds) {
;     ...
;     for (int r = 0; r < 16; ++r) { const int orow = crow(r, hi_e); float v[4]; float ss = 0.f;
; #pragma unroll
;       for (int d0 = 0; d0 < 4; ++d0) { v[d0] = o[d0][r] - lam * X[(wq_e * 32 + orow) * 128 + d0 * 32 + r32_e]; ss += v[d0] * v[d0]; }
;       ss += __shfl_xor(ss, 1); ss += __shfl_xor(ss, 2); ss += __shfl_xor(ss, 4); ss += __shfl_xor(ss, 8); ss += __shfl_xor(ss, 16);
;       const float rs = 1.0f / sqrtf(ss * (1.0f / 128.0f) + LN_EPS);
; #pragma unroll
;       for (int d0 = 0; d0 < 4; ++d0) Ow[(long)orow * DM + d0 * 32 + r32_e] = (bf16)f2bf(v[d0] * rs * sw[d0]); }
	v_add_f32_e32 v13, v13, v16
	s_nop 1
	v_mov_b32_dpp v16, v13 row_mirror row_mask:0xf bank_mask:0xf
	s_waitcnt lgkmcnt(0)
	v_add_f32_e32 v13, v13, v16
	v_mov_b32_e32 v16, v13
	s_nop 1
	v_permlane16_swap_b32_e32 v13, v16
	s_waitcnt lgkmcnt(0)
	v_add_f32_e32 v13, v13, v16
	v_fmamk_f32 v13, v13, 0x3c000000, v179
	v_cmp_gt_f32_e32 vcc, s4, v13
	v_mul_f32_e32 v16, 0x4f800000, v13
	s_nop 0
	v_cndmask_b32_e32 v13, v13, v16, vcc
	v_sqrt_f32_e32 v16, v13
	s_nop 0
	v_add_u32_e32 v17, -1, v16
	v_fma_f32 v18, -v17, v16, v13
	v_cmp_ge_f32_e64 s[0:1], 0, v18
	v_add_u32_e32 v18, 1, v16
	s_nop 0
	v_cndmask_b32_e64 v17, v16, v17, s[0:1]
	v_fma_f32 v16, -v18, v16, v13
	v_cmp_lt_f32_e64 s[0:1], 0, v16
	s_nop 1
	v_cndmask_b32_e64 v16, v17, v18, s[0:1]
	v_mul_f32_e32 v17, 0x37800000, v16
	v_cndmask_b32_e32 v16, v16, v17, vcc
	v_cmp_class_f32_e32 vcc, v13, v180
	s_nop 1
	v_cndmask_b32_e32 v13, v16, v13, vcc
	v_div_scale_f32 v16, s[0:1], v13, v13, 1.0
	v_rcp_f32_e32 v17, v16
	s_nop 0
	v_fma_f32 v18, -v16, v17, 1.0
	v_fmac_f32_e32 v17, v18, v17
	v_div_scale_f32 v18, vcc, 1.0, v13, 1.0
	v_mul_f32_e32 v19, v18, v17
	v_fma_f32 v20, -v16, v19, v18
	v_fmac_f32_e32 v19, v20, v17
	v_fma_f32 v16, -v16, v19, v18
	v_div_fmas_f32 v16, v16, v17, v19
	v_div_fixup_f32 v13, v16, v13, 1.0
	v_mul_f32_e32 v14, v14, v13
	v_mul_f32_e32 v14, v34, v14
	v_bfe_u32 v16, v14, 16, 1
	v_add3_u32 v14, v14, v16, s70
	global_store_short_d16_hi v[10:11], v14, off
	v_mul_f32_e32 v14, v15, v13
	v_mul_f32_e32 v14, v35, v14
	v_bfe_u32 v15, v14, 16, 1
	v_mul_f32_e32 v9, v9, v13
	v_add3_u32 v14, v14, v15, s70
	v_mul_f32_e32 v9, v36, v9
	global_store_short_d16_hi v[10:11], v14, off offset:64
	v_bfe_u32 v14, v9, 16, 1
	v_add3_u32 v9, v9, v14, s70
	global_store_short_d16_hi v[10:11], v9, off offset:128
	v_mul_f32_e32 v9, v12, v13
	v_mul_f32_e32 v9, v37, v9
	v_bfe_u32 v12, v9, 16, 1
	v_add3_u32 v9, v9, v12, s70
	global_store_short_d16_hi v[10:11], v9, off offset:192
	v_add_u32_e32 v9, v6, v8
	v_lshl_add_u32 v9, v9, 7, v138
	v_lshl_add_u32 v9, v9, 2, 0
	ds_read2_b32 v[10:11], v9 offset1:32
	v_lshlrev_b64 v[6:7], 12, v[6:7]
	v_lshl_add_u64 v[6:7], v[4:5], 0, v[6:7]
	s_waitcnt lgkmcnt(0)
	v_fma_f32 v12, -v160, v10, v67
	v_fma_f32 v13, -v160, v11, v51
	ds_read2_b32 v[10:11], v9 offset0:64 offset1:96
	v_mul_f32_e32 v14, v13, v13
	v_fmac_f32_e32 v14, v12, v12
	s_waitcnt lgkmcnt(0)
	v_fma_f32 v9, -v160, v10, v38
	v_fmac_f32_e32 v14, v9, v9
	v_fma_f32 v10, -v160, v11, v39
	v_fmac_f32_e32 v14, v10, v10
	s_nop 1
	v_mov_b32_dpp v11, v14 quad_perm:[1,0,3,2] row_mask:0xf bank_mask:0xf
	s_waitcnt lgkmcnt(0)
	v_add_f32_e32 v11, v14, v11
	s_nop 1
	v_mov_b32_dpp v14, v11 quad_perm:[2,3,0,1] row_mask:0xf bank_mask:0xf
	s_waitcnt lgkmcnt(0)
	v_add_f32_e32 v11, v11, v14
	s_nop 1
	v_mov_b32_dpp v14, v11 row_half_mirror row_mask:0xf bank_mask:0xf
	s_waitcnt lgkmcnt(0)
	v_add_f32_e32 v11, v11, v14
	s_nop 1
	v_mov_b32_dpp v14, v11 row_mirror row_mask:0xf bank_mask:0xf
	s_waitcnt lgkmcnt(0)
	v_add_f32_e32 v11, v11, v14
	v_mov_b32_e32 v14, v11
	s_nop 1
	v_permlane16_swap_b32_e32 v11, v14
	s_waitcnt lgkmcnt(0)
; __device__ __forceinline__ unsigned f2bf(float f) { unsigned u = __builtin_bit_cast(unsigned, f); return (u + 0x7fffu + ((u >> 16) & 1u)) >> 16; }
; __device__ __forceinline__ int crow(int r, int hi) { return (r & 3) + 8 * (r >> 2) + 4 * hi; }
; __device__ __forceinline__ void attn_unit(const bf16* __restrict__ Qb, const bf16* __restrict__ Kh, const bf16* __restrict__ Vh, int klat0, int nlt, int kctx0, int NT,
;                                           float lam, float post, const float* __restrict__ subw, bf16* __restrict__ Ob, char* lds) {
;     ...
;     for (int r = 0; r < 16; ++r) { const int orow = crow(r, hi_e); float v[4]; float ss = 0.f;
; #pragma unroll
;       for (int d0 = 0; d0 < 4; ++d0) { v[d0] = o[d0][r] - lam * X[(wq_e * 32 + orow) * 128 + d0 * 32 + r32_e]; ss += v[d0] * v[d0]; }
;       ss += __shfl_xor(ss, 1); ss += __shfl_xor(ss, 2); ss += __shfl_xor(ss, 4); ss += __shfl_xor(ss, 8); ss += __shfl_xor(ss, 16);
;       const float rs = 1.0f / sqrtf(ss * (1.0f / 128.0f) + LN_EPS);
; #pragma unroll
;       for (int d0 = 0; d0 < 4; ++d0) Ow[(long)orow * DM + d0 * 32 + r32_e] = (bf16)f2bf(v[d0] * rs * sw[d0]); }
	v_add_f32_e32 v11, v11, v14
	v_fmamk_f32 v11, v11, 0x3c000000, v179
	v_cmp_gt_f32_e32 vcc, s4, v11
	v_mul_f32_e32 v14, 0x4f800000, v11
	s_nop 0
	v_cndmask_b32_e32 v11, v11, v14, vcc
	v_sqrt_f32_e32 v14, v11
	s_nop 0
	v_add_u32_e32 v15, -1, v14
	v_fma_f32 v16, -v15, v14, v11
	v_cmp_ge_f32_e64 s[0:1], 0, v16
	v_add_u32_e32 v16, 1, v14
	s_nop 0
	v_cndmask_b32_e64 v15, v14, v15, s[0:1]
	v_fma_f32 v14, -v16, v14, v11
	v_cmp_lt_f32_e64 s[0:1], 0, v14
	s_nop 1
	v_cndmask_b32_e64 v14, v15, v16, s[0:1]
	v_mul_f32_e32 v15, 0x37800000, v14
	v_cndmask_b32_e32 v14, v14, v15, vcc
	v_cmp_class_f32_e32 vcc, v11, v180
	s_nop 1
	v_cndmask_b32_e32 v11, v14, v11, vcc
	v_div_scale_f32 v14, s[0:1], v11, v11, 1.0
	v_rcp_f32_e32 v15, v14
	s_nop 0
	v_fma_f32 v16, -v14, v15, 1.0
	v_fmac_f32_e32 v15, v16, v15
	v_div_scale_f32 v16, vcc, 1.0, v11, 1.0
	v_mul_f32_e32 v17, v16, v15
	v_fma_f32 v18, -v14, v17, v16
	v_fmac_f32_e32 v17, v18, v15
	v_fma_f32 v14, -v14, v17, v16
	v_div_fmas_f32 v14, v14, v15, v17
	v_div_fixup_f32 v11, v14, v11, 1.0
	v_mul_f32_e32 v12, v12, v11
	v_mul_f32_e32 v12, v34, v12
	v_bfe_u32 v14, v12, 16, 1
	v_add3_u32 v12, v12, v14, s70
	global_store_short_d16_hi v[6:7], v12, off
	v_mul_f32_e32 v12, v13, v11
	v_mul_f32_e32 v12, v35, v12
	v_bfe_u32 v13, v12, 16, 1
	v_mul_f32_e32 v9, v9, v11
	v_add3_u32 v12, v12, v13, s70
	v_mul_f32_e32 v9, v36, v9
	global_store_short_d16_hi v[6:7], v12, off offset:64
	v_bfe_u32 v12, v9, 16, 1
	v_add3_u32 v9, v9, v12, s70
	global_store_short_d16_hi v[6:7], v9, off offset:128
	v_mul_f32_e32 v9, v10, v11
	v_mul_f32_e32 v9, v37, v9
	v_bfe_u32 v10, v9, 16, 1
	v_add3_u32 v9, v9, v10, s70
	global_store_short_d16_hi v[6:7], v9, off offset:192
	v_add_u32_e32 v6, v2, v8
	v_lshl_add_u32 v6, v6, 7, v138
	v_lshl_add_u32 v8, v6, 2, 0
	ds_read2_b32 v[6:7], v8 offset1:32
	v_lshlrev_b64 v[2:3], 12, v[2:3]
	v_lshl_add_u64 v[2:3], v[4:5], 0, v[2:3]
	s_waitcnt lgkmcnt(0)
	v_fma_f32 v9, -v160, v6, v66
	v_fma_f32 v10, -v160, v7, v50
	ds_read2_b32 v[6:7], v8 offset0:64 offset1:96
	v_mul_f32_e32 v11, v10, v10
	v_fmac_f32_e32 v11, v9, v9
	s_waitcnt lgkmcnt(0)
	v_fma_f32 v6, -v160, v6, v32
	v_fmac_f32_e32 v11, v6, v6
	v_fma_f32 v7, -v160, v7, v33
	v_fmac_f32_e32 v11, v7, v7
	s_nop 1
	v_mov_b32_dpp v8, v11 quad_perm:[1,0,3,2] row_mask:0xf bank_mask:0xf
	s_waitcnt lgkmcnt(0)
	v_add_f32_e32 v8, v11, v8
	s_nop 1
	v_mov_b32_dpp v11, v8 quad_perm:[2,3,0,1] row_mask:0xf bank_mask:0xf
	s_waitcnt lgkmcnt(0)
	v_add_f32_e32 v8, v8, v11
	s_nop 1
	v_mov_b32_dpp v11, v8 row_half_mirror row_mask:0xf bank_mask:0xf
	s_waitcnt lgkmcnt(0)
	v_add_f32_e32 v8, v8, v11
	s_nop 1
	v_mov_b32_dpp v11, v8 row_mirror row_mask:0xf bank_mask:0xf
	s_waitcnt lgkmcnt(0)
	v_add_f32_e32 v8, v8, v11
	v_mov_b32_e32 v11, v8
	s_nop 1
	v_permlane16_swap_b32_e32 v8, v11
	s_waitcnt lgkmcnt(0)
	v_add_f32_e32 v8, v8, v11
	v_fmamk_f32 v8, v8, 0x3c000000, v179
	v_cmp_gt_f32_e32 vcc, s4, v8
	v_mul_f32_e32 v11, 0x4f800000, v8
	s_nop 0
	v_cndmask_b32_e32 v8, v8, v11, vcc
	v_sqrt_f32_e32 v11, v8
	s_nop 0
	v_add_u32_e32 v12, -1, v11
	v_fma_f32 v13, -v12, v11, v8
	v_cmp_ge_f32_e64 s[0:1], 0, v13
	v_add_u32_e32 v13, 1, v11
	s_nop 0
	v_cndmask_b32_e64 v12, v11, v12, s[0:1]
	v_fma_f32 v11, -v13, v11, v8
	v_cmp_lt_f32_e64 s[0:1], 0, v11
	s_nop 1
	v_cndmask_b32_e64 v11, v12, v13, s[0:1]
	v_mul_f32_e32 v12, 0x37800000, v11
	v_cndmask_b32_e32 v11, v11, v12, vcc
	v_cmp_class_f32_e32 vcc, v8, v180
	s_nop 1
	v_cndmask_b32_e32 v8, v11, v8, vcc
	v_div_scale_f32 v11, s[0:1], v8, v8, 1.0
	v_rcp_f32_e32 v12, v11
	s_nop 0
	v_fma_f32 v13, -v11, v12, 1.0
	v_fmac_f32_e32 v12, v13, v12
	v_div_scale_f32 v13, vcc, 1.0, v8, 1.0
	v_mul_f32_e32 v14, v13, v12
	v_fma_f32 v15, -v11, v14, v13
	v_fmac_f32_e32 v14, v15, v12
	v_fma_f32 v11, -v11, v14, v13
	v_div_fmas_f32 v11, v11, v12, v14
	v_div_fixup_f32 v8, v11, v8, 1.0
	v_mul_f32_e32 v4, v9, v8
	v_mul_f32_e32 v4, v34, v4
	v_bfe_u32 v5, v4, 16, 1
	v_add3_u32 v4, v4, v5, s70
	global_store_short_d16_hi v[2:3], v4, off
	v_mul_f32_e32 v4, v10, v8
	v_mul_f32_e32 v4, v35, v4
	v_bfe_u32 v5, v4, 16, 1
	v_add3_u32 v4, v4, v5, s70
	global_store_short_d16_hi v[2:3], v4, off offset:64
	v_mul_f32_e32 v4, v6, v8
	v_mul_f32_e32 v4, v36, v4
	v_bfe_u32 v5, v4, 16, 1
	v_add3_u32 v4, v4, v5, s70
	global_store_short_d16_hi v[2:3], v4, off offset:128
	v_mul_f32_e32 v4, v7, v8
	v_mul_f32_e32 v4, v37, v4
	v_bfe_u32 v5, v4, 16, 1
	v_add3_u32 v4, v4, v5, s70
	global_store_short_d16_hi v[2:3], v4, off offset:192
	s_branch .LBB0_714
